# norm loop: the two rows' wave-sum butterfly chains interleaved (two ds_bpermute in flight per hop), same operations and order per chain
# speedup vs baseline: 1.0067x; 1.0018x over previous
; DEVQ unsigned pk2(float lo, float hi) { return f2bf(lo) | (f2bf(hi) << 16); }
; DEVQ float wave_sum(float v) {
; #pragma unroll
;     for (int o = 1; o < 64; o <<= 1) v += __shfl_xor(v, o);
;     return v;
; }
; DEVQ void row_finish(const RowV& r, const float* g, bf16* urow, float* hcopy, const float* hbias, int lane) {
;     const float rstd = 1.0f / sqrtf(wave_sum(r.ss) * (1.0f / D) + RMS_EPS);
; #pragma unroll
;     for (int j = 0; j < 4; ++j) { const f32x4 gv = ((const f32x4*)g)[lane + 64 * j];
;         if (hcopy) ((f32x4*)hcopy)[lane + 64 * j] = r.v[j] + ((const f32x4*)hbias)[lane + 64 * j];
;         ((unsigned long long*)urow)[lane + 64 * j] = (unsigned long long)pk2(r.v[j].x * rstd * gv.x, r.v[j].y * rstd * gv.y) | ((unsigned long long)pk2(r.v[j].z * rstd * gv.z, r.v[j].w * rstd * gv.w) << 32); }
; }
.LBB0_183:
	v_lshl_add_u64 v[0:1], s[18:19], 0, v[42:43]
	v_add_co_u32_e32 v2, vcc, 0x3200000, v0
	s_addk_i32 s4, 0x780
	s_nop 0
	v_addc_co_u32_e32 v3, vcc, 0, v1, vcc
	flat_load_dwordx4 v[28:31], v[2:3]
	flat_load_dwordx4 v[24:27], v[2:3] offset:1024
	flat_load_dwordx4 v[20:23], v[2:3] offset:2048
	flat_load_dwordx4 v[16:19], v[2:3] offset:3072
	v_add_co_u32_e32 v0, vcc, s30, v0
	v_lshl_add_u64 v[42:43], v[42:43], 0, s[14:15]
	s_nop 0
	v_addc_co_u32_e32 v1, vcc, 0, v1, vcc
	s_cmp_gt_i32 s4, 0x987f
	s_waitcnt vmcnt(0) lgkmcnt(0)
	v_mul_f32_e32 v2, v29, v29
	v_mul_f32_e32 v3, v31, v31
	v_fmac_f32_e32 v2, v28, v28
	v_fmac_f32_e32 v3, v30, v30
	v_add_f32_e32 v2, v2, v3
	v_mul_f32_e32 v3, v25, v25
	v_mul_f32_e32 v4, v27, v27
	v_fmac_f32_e32 v3, v24, v24
	v_fmac_f32_e32 v4, v26, v26
	v_add_f32_e32 v3, v3, v4
	v_add_f32_e32 v2, v2, v3
	v_mul_f32_e32 v3, v21, v21
	v_mul_f32_e32 v4, v23, v23
	v_fmac_f32_e32 v3, v20, v20
	v_fmac_f32_e32 v4, v22, v22
	v_add_f32_e32 v3, v3, v4
	v_add_f32_e32 v2, v2, v3
	v_mul_f32_e32 v3, v17, v17
	v_mul_f32_e32 v4, v19, v19
	v_fmac_f32_e32 v3, v16, v16
	v_fmac_f32_e32 v4, v18, v18
	v_add_f32_e32 v3, v3, v4
	v_add_f32_e32 v51, v2, v3
	flat_load_dwordx4 v[12:15], v[0:1]
	flat_load_dwordx4 v[8:11], v[0:1] offset:1024
	flat_load_dwordx4 v[4:7], v[0:1] offset:2048
	s_nop 0
	flat_load_dwordx4 v[0:3], v[0:1] offset:3072
	s_waitcnt vmcnt(0) lgkmcnt(0)
	v_mul_f32_e32 v50, v13, v13
	v_mul_f32_e32 v52, v15, v15
	v_fmac_f32_e32 v50, v12, v12
	v_fmac_f32_e32 v52, v14, v14
	v_add_f32_e32 v50, v50, v52
	v_mul_f32_e32 v52, v9, v9
	v_mul_f32_e32 v53, v11, v11
	v_fmac_f32_e32 v52, v8, v8
	v_fmac_f32_e32 v53, v10, v10
	v_add_f32_e32 v52, v52, v53
	v_add_f32_e32 v50, v50, v52
	v_mul_f32_e32 v52, v5, v5
	v_mul_f32_e32 v53, v7, v7
	v_fmac_f32_e32 v52, v4, v4
	v_fmac_f32_e32 v53, v6, v6
	v_add_f32_e32 v52, v52, v53
	v_add_f32_e32 v50, v50, v52
	v_mul_f32_e32 v52, v1, v1
	v_mul_f32_e32 v53, v3, v3
	v_fmac_f32_e32 v52, v0, v0
	v_fmac_f32_e32 v53, v2, v2
	v_add_f32_e32 v52, v52, v53
	v_add_f32_e32 v50, v50, v52
	ds_bpermute_b32 v52, v44, v51
	ds_bpermute_b32 v97, v44, v50
	s_waitcnt lgkmcnt(0)
	v_add_f32_e32 v51, v51, v52
	v_add_f32_e32 v96, v50, v97
	ds_bpermute_b32 v52, v45, v51
	ds_bpermute_b32 v97, v45, v96
	s_waitcnt lgkmcnt(0)
	v_add_f32_e32 v51, v51, v52
	v_add_f32_e32 v96, v96, v97
	ds_bpermute_b32 v52, v46, v51
	ds_bpermute_b32 v97, v46, v96
	s_waitcnt lgkmcnt(0)
	v_add_f32_e32 v51, v51, v52
	v_add_f32_e32 v96, v96, v97
	ds_bpermute_b32 v52, v47, v51
	ds_bpermute_b32 v97, v47, v96
	s_waitcnt lgkmcnt(0)
	v_add_f32_e32 v51, v51, v52
	v_add_f32_e32 v96, v96, v97
	ds_bpermute_b32 v52, v48, v51
	ds_bpermute_b32 v97, v48, v96
	s_waitcnt lgkmcnt(0)
	v_add_f32_e32 v51, v51, v52
	v_add_f32_e32 v96, v96, v97
	ds_bpermute_b32 v52, v49, v51
	ds_bpermute_b32 v97, v49, v96
	s_waitcnt lgkmcnt(0)
	v_add_f32_e32 v51, v51, v52
	v_add_f32_e32 v96, v96, v97
	v_fmamk_f32 v51, v51, 0x3a800000, v178
	v_cmp_gt_f32_e32 vcc, s28, v51
	v_mul_f32_e32 v52, 0x4f800000, v51
	s_nop 0
	v_cndmask_b32_e32 v51, v51, v52, vcc
	v_sqrt_f32_e32 v52, v51
	s_nop 0
	v_add_u32_e32 v53, -1, v52
	v_fma_f32 v54, -v53, v52, v51
	v_cmp_ge_f32_e64 s[0:1], 0, v54
	v_add_u32_e32 v54, 1, v52
	s_nop 0
	v_cndmask_b32_e64 v53, v52, v53, s[0:1]
	v_fma_f32 v52, -v54, v52, v51
	v_cmp_lt_f32_e64 s[0:1], 0, v52
	s_nop 1
	v_cndmask_b32_e64 v52, v53, v54, s[0:1]
	v_mul_f32_e32 v53, 0x37800000, v52
	v_cndmask_b32_e32 v52, v52, v53, vcc
	v_cmp_class_f32_e32 vcc, v51, v179
	s_nop 1
	v_cndmask_b32_e32 v51, v52, v51, vcc
	v_div_scale_f32 v52, s[0:1], v51, v51, 1.0
	v_rcp_f32_e32 v53, v52
	s_nop 0
	v_fma_f32 v54, -v52, v53, 1.0
	v_fmac_f32_e32 v53, v54, v53
	v_div_scale_f32 v54, vcc, 1.0, v51, 1.0
	v_mul_f32_e32 v55, v54, v53
	v_fma_f32 v56, -v52, v55, v54
	v_fmac_f32_e32 v55, v56, v53
	v_fma_f32 v52, -v52, v55, v54
	v_div_fmas_f32 v52, v52, v53, v55
	v_div_fixup_f32 v51, v52, v51, 1.0
	v_mul_f32_e32 v28, v28, v51
	v_mul_f32_e32 v29, v29, v51
	v_mul_f32_e32 v24, v24, v51
	v_mul_f32_e32 v25, v25, v51
	v_mul_f32_e32 v20, v20, v51
	v_mul_f32_e32 v21, v21, v51
	v_mul_f32_e32 v16, v16, v51
	v_mul_f32_e32 v17, v17, v51
	v_mul_f32_e32 v28, v64, v28
	v_mul_f32_e32 v29, v65, v29
	v_bfe_u32 v52, v28, 16, 1
	v_add3_u32 v28, v28, v52, s60
	v_bfe_u32 v52, v29, 16, 1
	v_lshrrev_b32_e32 v28, 16, v28
	v_add3_u32 v29, v29, v52, s60
	v_and_or_b32 v52, v29, s61, v28
	v_mul_f32_e32 v28, v30, v51
	v_mul_f32_e32 v28, v66, v28
	v_mul_f32_e32 v29, v31, v51
	v_mul_f32_e32 v29, v67, v29
	v_bfe_u32 v30, v28, 16, 1
	v_add3_u32 v28, v28, v30, s60
	v_bfe_u32 v30, v29, 16, 1
	v_lshrrev_b32_e32 v28, 16, v28
	v_add3_u32 v29, v29, v30, s60
	v_and_or_b32 v53, v29, s61, v28
	v_lshl_add_u64 v[28:29], s[18:19], 0, v[40:41]
	v_add_co_u32_e32 v28, vcc, s31, v28
	s_nop 1
	v_addc_co_u32_e32 v29, vcc, 0, v29, vcc
	flat_store_dwordx2 v[28:29], v[52:53]
	v_mul_f32_e32 v24, v68, v24
	v_mul_f32_e32 v25, v69, v25
	v_bfe_u32 v30, v24, 16, 1
	v_add3_u32 v24, v24, v30, s60
	v_bfe_u32 v30, v25, 16, 1
	v_lshrrev_b32_e32 v24, 16, v24
	v_add3_u32 v25, v25, v30, s60
	v_and_or_b32 v24, v25, s61, v24
; DEVQ unsigned pk2(float lo, float hi) { return f2bf(lo) | (f2bf(hi) << 16); }
; DEVQ void row_finish(const RowV& r, const float* g, bf16* urow, float* hcopy, const float* hbias, int lane) {
;     const float rstd = 1.0f / sqrtf(wave_sum(r.ss) * (1.0f / D) + RMS_EPS);
; #pragma unroll
;     for (int j = 0; j < 4; ++j) { const f32x4 gv = ((const f32x4*)g)[lane + 64 * j];
;         if (hcopy) ((f32x4*)hcopy)[lane + 64 * j] = r.v[j] + ((const f32x4*)hbias)[lane + 64 * j];
;         ((unsigned long long*)urow)[lane + 64 * j] = (unsigned long long)pk2(r.v[j].x * rstd * gv.x, r.v[j].y * rstd * gv.y) | ((unsigned long long)pk2(r.v[j].z * rstd * gv.z, r.v[j].w * rstd * gv.w) << 32); }
; }
	v_mul_f32_e32 v25, v26, v51
	v_mul_f32_e32 v25, v70, v25
	v_mul_f32_e32 v26, v27, v51
	v_mul_f32_e32 v26, v71, v26
	v_bfe_u32 v27, v25, 16, 1
	v_add3_u32 v25, v25, v27, s60
	v_bfe_u32 v27, v26, 16, 1
	v_lshrrev_b32_e32 v25, 16, v25
	v_add3_u32 v26, v26, v27, s60
	v_and_or_b32 v25, v26, s61, v25
	flat_store_dwordx2 v[28:29], v[24:25] offset:512
	v_mul_f32_e32 v20, v72, v20
	v_mul_f32_e32 v21, v73, v21
	v_bfe_u32 v24, v20, 16, 1
	v_add3_u32 v20, v20, v24, s60
	v_bfe_u32 v24, v21, 16, 1
	v_lshrrev_b32_e32 v20, 16, v20
	v_add3_u32 v21, v21, v24, s60
	v_and_or_b32 v20, v21, s61, v20
	v_mul_f32_e32 v21, v22, v51
	v_mul_f32_e32 v21, v74, v21
	v_mul_f32_e32 v22, v23, v51
	v_mul_f32_e32 v22, v75, v22
	v_bfe_u32 v23, v21, 16, 1
	v_add3_u32 v21, v21, v23, s60
	v_bfe_u32 v23, v22, 16, 1
	v_lshrrev_b32_e32 v21, 16, v21
	v_add3_u32 v22, v22, v23, s60
	v_and_or_b32 v21, v22, s61, v21
	flat_store_dwordx2 v[28:29], v[20:21] offset:1024
	v_mul_f32_e32 v16, v16, v76
	v_mul_f32_e32 v17, v17, v77
	v_bfe_u32 v20, v16, 16, 1
	v_add3_u32 v16, v16, v20, s60
	v_bfe_u32 v20, v17, 16, 1
	v_lshrrev_b32_e32 v16, 16, v16
	v_add3_u32 v17, v17, v20, s60
	v_and_or_b32 v16, v17, s61, v16
	v_mul_f32_e32 v17, v18, v51
	v_mul_f32_e32 v17, v17, v78
	v_mul_f32_e32 v18, v19, v51
	v_mul_f32_e32 v18, v18, v79
	v_bfe_u32 v19, v17, 16, 1
	v_add3_u32 v17, v17, v19, s60
	v_bfe_u32 v19, v18, 16, 1
	v_lshrrev_b32_e32 v17, 16, v17
	v_add3_u32 v18, v18, v19, s60
	v_and_or_b32 v17, v18, s61, v17
	flat_store_dwordx2 v[28:29], v[16:17] offset:1536
	v_mov_b32_e32 v16, v96
	v_fmamk_f32 v16, v16, 0x3a800000, v178
	v_cmp_gt_f32_e32 vcc, s28, v16
	v_mul_f32_e32 v17, 0x4f800000, v16
	s_nop 0
	v_cndmask_b32_e32 v16, v16, v17, vcc
	v_sqrt_f32_e32 v17, v16
	s_nop 0
	v_add_u32_e32 v18, -1, v17
	v_fma_f32 v19, -v18, v17, v16
	v_cmp_ge_f32_e64 s[0:1], 0, v19
	v_add_u32_e32 v19, 1, v17
	s_nop 0
	v_cndmask_b32_e64 v18, v17, v18, s[0:1]
	v_fma_f32 v17, -v19, v17, v16
	v_cmp_lt_f32_e64 s[0:1], 0, v17
	s_nop 1
	v_cndmask_b32_e64 v17, v18, v19, s[0:1]
	v_mul_f32_e32 v18, 0x37800000, v17
	v_cndmask_b32_e32 v17, v17, v18, vcc
	v_cmp_class_f32_e32 vcc, v16, v179
	s_nop 1
	v_cndmask_b32_e32 v16, v17, v16, vcc
	v_div_scale_f32 v17, s[0:1], v16, v16, 1.0
	v_rcp_f32_e32 v18, v17
	s_mov_b64 s[0:1], 0x3c0000
	v_lshl_add_u64 v[40:41], v[40:41], 0, s[0:1]
	v_fma_f32 v19, -v17, v18, 1.0
	v_fmac_f32_e32 v18, v19, v18
	v_div_scale_f32 v19, vcc, 1.0, v16, 1.0
	v_mul_f32_e32 v20, v19, v18
	v_fma_f32 v21, -v17, v20, v19
	v_fmac_f32_e32 v20, v21, v18
	v_fma_f32 v17, -v17, v20, v19
	v_div_fmas_f32 v17, v17, v18, v20
	v_div_fixup_f32 v16, v17, v16, 1.0
	v_mul_f32_e32 v12, v12, v16
	v_mul_f32_e32 v13, v13, v16
	v_mul_f32_e32 v8, v8, v16
	v_mul_f32_e32 v9, v9, v16
	v_mul_f32_e32 v4, v4, v16
	v_mul_f32_e32 v5, v5, v16
	v_mul_f32_e32 v0, v0, v16
	v_mul_f32_e32 v1, v1, v16
	v_mul_f32_e32 v12, v64, v12
	v_mul_f32_e32 v13, v65, v13
	v_bfe_u32 v17, v12, 16, 1
	v_add3_u32 v12, v12, v17, s60
	v_bfe_u32 v17, v13, 16, 1
	v_lshrrev_b32_e32 v12, 16, v12
	v_add3_u32 v13, v13, v17, s60
	v_and_or_b32 v12, v13, s61, v12
	v_mul_f32_e32 v13, v14, v16
	v_mul_f32_e32 v13, v66, v13
	v_mul_f32_e32 v14, v15, v16
	v_mul_f32_e32 v14, v67, v14
	v_bfe_u32 v15, v13, 16, 1
	v_add3_u32 v13, v13, v15, s60
	v_bfe_u32 v15, v14, 16, 1
	v_lshrrev_b32_e32 v13, 16, v13
	v_add3_u32 v14, v14, v15, s60
	v_and_or_b32 v13, v14, s61, v13
	flat_store_dwordx2 v[28:29], v[12:13] offset:2048
	v_mul_f32_e32 v8, v68, v8
	v_mul_f32_e32 v9, v69, v9
	v_bfe_u32 v12, v8, 16, 1
	v_add3_u32 v8, v8, v12, s60
	v_bfe_u32 v12, v9, 16, 1
	v_lshrrev_b32_e32 v8, 16, v8
	v_add3_u32 v9, v9, v12, s60
	v_and_or_b32 v8, v9, s61, v8
	v_mul_f32_e32 v9, v10, v16
	v_mul_f32_e32 v9, v70, v9
	v_mul_f32_e32 v10, v11, v16
	v_mul_f32_e32 v10, v71, v10
	v_bfe_u32 v11, v9, 16, 1
	v_add3_u32 v9, v9, v11, s60
	v_bfe_u32 v11, v10, 16, 1
	v_lshrrev_b32_e32 v9, 16, v9
	v_add3_u32 v10, v10, v11, s60
	v_and_or_b32 v9, v10, s61, v9
	flat_store_dwordx2 v[28:29], v[8:9] offset:2560
	v_mul_f32_e32 v4, v72, v4
	v_mul_f32_e32 v5, v73, v5
	v_bfe_u32 v8, v4, 16, 1
	v_add3_u32 v4, v4, v8, s60
	v_bfe_u32 v8, v5, 16, 1
	v_lshrrev_b32_e32 v4, 16, v4
	v_add3_u32 v5, v5, v8, s60
	v_and_or_b32 v4, v5, s61, v4
	v_mul_f32_e32 v5, v6, v16
	v_mul_f32_e32 v5, v74, v5
	v_mul_f32_e32 v6, v7, v16
	v_mul_f32_e32 v6, v75, v6
	v_bfe_u32 v7, v5, 16, 1
	v_add3_u32 v5, v5, v7, s60
	v_bfe_u32 v7, v6, 16, 1
	v_lshrrev_b32_e32 v5, 16, v5
	v_add3_u32 v6, v6, v7, s60
	v_and_or_b32 v5, v6, s61, v5
	flat_store_dwordx2 v[28:29], v[4:5] offset:3072
	v_mul_f32_e32 v0, v0, v76
	v_mul_f32_e32 v1, v1, v77
	v_bfe_u32 v4, v0, 16, 1
	v_add3_u32 v0, v0, v4, s60
	v_bfe_u32 v4, v1, 16, 1
	v_lshrrev_b32_e32 v0, 16, v0
	v_add3_u32 v1, v1, v4, s60
	v_and_or_b32 v0, v1, s61, v0
	v_mul_f32_e32 v1, v2, v16
	v_mul_f32_e32 v1, v1, v78
	v_mul_f32_e32 v2, v3, v16
	v_mul_f32_e32 v2, v2, v79
	v_bfe_u32 v3, v1, 16, 1
	v_add3_u32 v1, v1, v3, s60
	v_bfe_u32 v3, v2, 16, 1
	v_lshrrev_b32_e32 v1, 16, v1
	v_add3_u32 v2, v2, v3, s60
	v_and_or_b32 v1, v2, s61, v1
	flat_store_dwordx2 v[28:29], v[0:1] offset:3584
	s_cbranch_scc0 .LBB0_183
